# SWA prompt q-tile: fmaxf canonicalising v_max_f32 x,x folded into the consuming v_max_f32 (109 VALU fewer per q-tile; VALU-bound loop), on top of v80
# speedup vs baseline: 1.0096x; 1.0096x over previous
; __device__ __forceinline__ void swa_prompt_unit(const Args& a, unsigned char* lds, int unit, int tid) {
;     ...
;         float mx = -3.0e38f;
; #pragma unroll
;         for (int t = 0; t < 16; ++t) if (t >= t0 && t <= t0 + 8) {
; #pragma unroll
;             for (int j = 0; j < 4; ++j) { const int key = t * 16 + q4 * 4 + j; const bool ok = key > qi && key <= qi + 128 && (blk > 0 || key >= 128); if (ok) mx = fmaxf(mx, sc[t][j]); } }
.LBB0_319:
	v_cmp_gt_u32_e64 s[0:1], v136, v191
	v_max_f32_e32 v1, v66, v34
	s_and_b64 s[0:1], s[16:17], s[0:1]
	v_cndmask_b32_e64 v1, v66, v1, s[0:1]
	v_cmp_gt_u32_e64 s[0:1], v137, v191
	v_max_f32_e32 v66, v1, v35
	s_and_b64 s[0:1], s[16:17], s[0:1]
	v_cndmask_b32_e64 v1, v1, v66, s[0:1]
	v_cmp_gt_u32_e64 s[0:1], v138, v191
	v_max_f32_e32 v66, v1, v36
	s_and_b64 s[0:1], s[16:17], s[0:1]
	v_cndmask_b32_e64 v1, v1, v66, s[0:1]
	v_cmp_gt_u32_e64 s[0:1], v139, v191
	v_max_f32_e32 v67, v37, v37
	v_max_f32_e32 v66, v1, v67
	s_and_b64 s[0:1], s[16:17], s[0:1]
	v_cndmask_b32_e64 v66, v1, v66, s[0:1]
.LBB0_320:
	s_or_b64 exec, exec, s[46:47]
	v_cmp_gt_u32_e64 s[0:1], v140, v191
	v_max_f32_e32 v67, v66, v42
	s_and_b64 s[46:47], s[16:17], s[0:1]
	v_cndmask_b32_e64 v66, v66, v67, s[46:47]
	v_cmp_gt_u32_e64 s[0:1], v141, v191
	v_max_f32_e32 v67, v66, v43
	s_and_b64 s[56:57], s[16:17], s[0:1]
	v_cndmask_b32_e64 v66, v66, v67, s[56:57]
	v_cmp_gt_u32_e64 s[0:1], v142, v191
	v_max_f32_e32 v67, v66, v44
	s_and_b64 s[50:51], s[16:17], s[0:1]
	v_cndmask_b32_e64 v66, v66, v67, s[50:51]
	v_cmp_gt_u32_e64 s[0:1], v143, v191
	v_max_f32_e32 v67, v66, v45
	s_and_b64 s[60:61], s[16:17], s[0:1]
	v_cndmask_b32_e64 v66, v66, v67, s[60:61]
	v_max_f32_e32 v67, v66, v38
	v_cmp_gt_u32_e64 s[52:53], v108, v191
	v_add_u32_e32 v1, 0x80, v191
	v_cndmask_b32_e64 v66, v67, v66, s[52:53]
	v_max_f32_e32 v67, v66, v39
	v_cmp_gt_u32_e64 s[58:59], v144, v1
	v_cmp_gt_u32_e64 s[48:49], v145, v1
	v_cndmask_b32_e64 v66, v67, v66, s[58:59]
	v_max_f32_e32 v67, v66, v40
	v_cndmask_b32_e64 v66, v67, v66, s[48:49]
	v_max_f32_e32 v68, v41, v41
	v_max_f32_e32 v67, v66, v68
	v_cmp_gt_u32_e64 s[54:55], v146, v1
	s_nop 1
	v_cndmask_b32_e64 v67, v67, v66, s[54:55]
	s_and_saveexec_b64 s[96:97], vcc
	s_cbranch_execnz .LBB0_370
	s_or_b64 exec, exec, s[96:97]
	s_and_saveexec_b64 s[96:97], s[22:23]
	s_cbranch_execnz .LBB0_371

; __device__ __forceinline__ void swa_prompt_unit(const Args& a, unsigned char* lds, int unit, int tid) {
;     ...
;         for (int t = 0; t < 16; ++t) if (t >= t0 && t <= t0 + 8) {
; #pragma unroll
;             for (int j = 0; j < 4; ++j) { const int key = t * 16 + q4 * 4 + j; const bool ok = key > qi && key <= qi + 128 && (blk > 0 || key >= 128); if (ok) mx = fmaxf(mx, sc[t][j]); } }
.LBB0_327:
	v_max_f32_e32 v66, v67, v2
	v_cmp_gt_u32_e64 s[0:1], v173, v1
	s_nop 0
	v_cndmask_b32_e64 v66, v66, v67, s[0:1]
	v_max_f32_e32 v67, v66, v3
	v_cmp_gt_u32_e64 s[0:1], v174, v1
	s_nop 0
	v_cndmask_b32_e64 v66, v67, v66, s[0:1]
	v_max_f32_e32 v67, v66, v4
	v_cmp_gt_u32_e64 s[0:1], v175, v1
	v_max_f32_e32 v68, v5, v5
	s_nop 0
	v_cndmask_b32_e64 v66, v67, v66, s[0:1]
	v_max_f32_e32 v67, v66, v68
	v_cmp_gt_u32_e64 s[0:1], v176, v1
	s_nop 1
	v_cndmask_b32_e64 v67, v67, v66, s[0:1]

; __device__ __forceinline__ void swa_prompt_unit(const Args& a, unsigned char* lds, int unit, int tid) {
;     ...
;         float mx = -3.0e38f;
; #pragma unroll
;         for (int t = 0; t < 16; ++t) if (t >= t0 && t <= t0 + 8) {
; #pragma unroll
;             for (int j = 0; j < 4; ++j) { const int key = t * 16 + q4 * 4 + j; const bool ok = key > qi && key <= qi + 128 && (blk > 0 || key >= 128); if (ok) mx = fmaxf(mx, sc[t][j]); } }
.LBB0_364:
	v_cmp_gt_u32_e64 s[0:1], v108, v191
	v_max_f32_e32 v1, v62, v62
	v_max_f32_e32 v1, 0xff61b1e6, v1
	s_and_b64 s[0:1], s[16:17], s[0:1]
	v_cndmask_b32_e64 v1, v190, v1, s[0:1]
	v_cmp_ge_u32_e64 s[0:1], v108, v191
	v_max_f32_e32 v66, v1, v63
	s_and_b64 s[0:1], s[16:17], s[0:1]
	v_cndmask_b32_e64 v1, v1, v66, s[0:1]
	v_cmp_gt_u32_e64 s[0:1], v109, v191
	v_max_f32_e32 v66, v1, v64
	s_and_b64 s[0:1], s[16:17], s[0:1]
	v_cndmask_b32_e64 v1, v1, v66, s[0:1]
	v_cmp_gt_u32_e64 s[0:1], v110, v191
	v_max_f32_e32 v66, v1, v65
	s_and_b64 s[0:1], s[16:17], s[0:1]
	v_cndmask_b32_e64 v66, v1, v66, s[0:1]
	s_or_b64 exec, exec, s[46:47]
	s_and_saveexec_b64 s[46:47], s[28:29]
	s_cbranch_execz .LBB0_314
.LBB0_365:
	v_cmp_gt_u32_e64 s[0:1], v111, v191
	v_max_f32_e32 v1, v66, v54
	s_and_b64 s[0:1], s[16:17], s[0:1]
	v_cndmask_b32_e64 v1, v66, v1, s[0:1]
	v_cmp_gt_u32_e64 s[0:1], v112, v191
	v_max_f32_e32 v66, v1, v55
	s_and_b64 s[0:1], s[16:17], s[0:1]
	v_cndmask_b32_e64 v1, v1, v66, s[0:1]
	v_cmp_gt_u32_e64 s[0:1], v113, v191
	v_max_f32_e32 v66, v1, v56
	s_and_b64 s[0:1], s[16:17], s[0:1]
	v_cndmask_b32_e64 v1, v1, v66, s[0:1]
	v_cmp_gt_u32_e64 s[0:1], v114, v191
	v_max_f32_e32 v67, v57, v57
	v_max_f32_e32 v66, v1, v67
	s_and_b64 s[0:1], s[16:17], s[0:1]
	v_cndmask_b32_e64 v66, v1, v66, s[0:1]
	s_or_b64 exec, exec, s[46:47]
	s_and_saveexec_b64 s[46:47], s[42:43]
	s_cbranch_execz .LBB0_315
.LBB0_366:
	v_cmp_gt_u32_e64 s[0:1], v115, v191
	v_max_f32_e32 v1, v66, v58
	s_and_b64 s[0:1], s[16:17], s[0:1]
	v_cndmask_b32_e64 v1, v66, v1, s[0:1]
	v_cmp_gt_u32_e64 s[0:1], v116, v191
	v_max_f32_e32 v66, v1, v59
	s_and_b64 s[0:1], s[16:17], s[0:1]
	v_cndmask_b32_e64 v1, v1, v66, s[0:1]
	v_cmp_gt_u32_e64 s[0:1], v117, v191
	v_max_f32_e32 v66, v1, v60
	s_and_b64 s[0:1], s[16:17], s[0:1]
	v_cndmask_b32_e64 v1, v1, v66, s[0:1]
	v_cmp_gt_u32_e64 s[0:1], v118, v191
	v_max_f32_e32 v67, v61, v61
	v_max_f32_e32 v66, v1, v67
	s_and_b64 s[0:1], s[16:17], s[0:1]
	v_cndmask_b32_e64 v66, v1, v66, s[0:1]
	s_or_b64 exec, exec, s[46:47]
	s_and_saveexec_b64 s[46:47], s[26:27]
	s_cbranch_execz .LBB0_316
.LBB0_367:
	v_cmp_gt_u32_e64 s[0:1], v119, v191
	v_max_f32_e32 v1, v66, v46
	s_and_b64 s[0:1], s[16:17], s[0:1]
	v_cndmask_b32_e64 v1, v66, v1, s[0:1]
	v_cmp_gt_u32_e64 s[0:1], v120, v191
	v_max_f32_e32 v66, v1, v47
	s_and_b64 s[0:1], s[16:17], s[0:1]
	v_cndmask_b32_e64 v1, v1, v66, s[0:1]
	v_cmp_gt_u32_e64 s[0:1], v121, v191
	v_max_f32_e32 v66, v1, v48
	s_and_b64 s[0:1], s[16:17], s[0:1]
	v_cndmask_b32_e64 v1, v1, v66, s[0:1]
	v_cmp_gt_u32_e64 s[0:1], v122, v191
	v_max_f32_e32 v67, v49, v49
	v_max_f32_e32 v66, v1, v67
	s_and_b64 s[0:1], s[16:17], s[0:1]
	v_cndmask_b32_e64 v66, v1, v66, s[0:1]
	s_or_b64 exec, exec, s[46:47]
	s_and_saveexec_b64 s[46:47], s[40:41]
	s_cbranch_execz .LBB0_317
.LBB0_368:
	v_cmp_gt_u32_e64 s[0:1], v123, v191
	v_max_f32_e32 v1, v66, v50
	s_and_b64 s[0:1], s[16:17], s[0:1]
	v_cndmask_b32_e64 v1, v66, v1, s[0:1]
	v_cmp_gt_u32_e64 s[0:1], v129, v191
	v_max_f32_e32 v66, v1, v51
	s_and_b64 s[0:1], s[16:17], s[0:1]
	v_cndmask_b32_e64 v1, v1, v66, s[0:1]
	v_cmp_gt_u32_e64 s[0:1], v130, v191
	v_max_f32_e32 v66, v1, v52
	s_and_b64 s[0:1], s[16:17], s[0:1]
	v_cndmask_b32_e64 v1, v1, v66, s[0:1]
	v_cmp_gt_u32_e64 s[0:1], v131, v191
	v_max_f32_e32 v67, v53, v53
	v_max_f32_e32 v66, v1, v67
	s_and_b64 s[0:1], s[16:17], s[0:1]
	v_cndmask_b32_e64 v66, v1, v66, s[0:1]
	s_or_b64 exec, exec, s[46:47]
	s_and_saveexec_b64 s[46:47], s[24:25]
	s_cbranch_execz .LBB0_318
.LBB0_369:
	v_cmp_gt_u32_e64 s[0:1], v132, v191
	v_max_f32_e32 v1, v66, v30
	s_and_b64 s[0:1], s[16:17], s[0:1]
	v_cndmask_b32_e64 v1, v66, v1, s[0:1]
	v_cmp_gt_u32_e64 s[0:1], v133, v191
	v_max_f32_e32 v66, v1, v31
	s_and_b64 s[0:1], s[16:17], s[0:1]
	v_cndmask_b32_e64 v1, v1, v66, s[0:1]
	v_cmp_gt_u32_e64 s[0:1], v134, v191
	v_max_f32_e32 v66, v1, v32
	s_and_b64 s[0:1], s[16:17], s[0:1]
	v_cndmask_b32_e64 v1, v1, v66, s[0:1]
	v_cmp_gt_u32_e64 s[0:1], v135, v191
	v_max_f32_e32 v67, v33, v33
	v_max_f32_e32 v66, v1, v67
	s_and_b64 s[0:1], s[16:17], s[0:1]
	v_cndmask_b32_e64 v66, v1, v66, s[0:1]
	s_or_b64 exec, exec, s[46:47]
	s_and_saveexec_b64 s[46:47], s[38:39]
	s_cbranch_execnz .LBB0_319
	s_branch .LBB0_320
; __device__ __forceinline__ void swa_prompt_unit(const Args& a, unsigned char* lds, int unit, int tid) {
;     ...
;         for (int t = 0; t < 16; ++t) if (t >= t0 && t <= t0 + 8) {
; #pragma unroll
;             for (int j = 0; j < 4; ++j) { const int key = t * 16 + q4 * 4 + j; const bool ok = key > qi && key <= qi + 128 && (blk > 0 || key >= 128); if (ok) mx = fmaxf(mx, sc[t][j]); } }
.LBB0_370:
	v_max_f32_e32 v66, v67, v26
	v_cmp_gt_u32_e64 s[0:1], v147, v1
	s_nop 0
	v_cndmask_b32_e64 v66, v66, v67, s[0:1]
	v_max_f32_e32 v67, v66, v27
	v_cmp_gt_u32_e64 s[0:1], v149, v1
	s_nop 0
	v_cndmask_b32_e64 v66, v67, v66, s[0:1]
	v_max_f32_e32 v67, v66, v28
	v_cmp_gt_u32_e64 s[0:1], v150, v1
	v_max_f32_e32 v68, v29, v29
	s_nop 0
	v_cndmask_b32_e64 v66, v67, v66, s[0:1]
	v_max_f32_e32 v67, v66, v68
	v_cmp_gt_u32_e64 s[0:1], v152, v1
	s_nop 1
	v_cndmask_b32_e64 v67, v67, v66, s[0:1]
	s_or_b64 exec, exec, s[96:97]
	s_and_saveexec_b64 s[96:97], s[22:23]
	s_cbranch_execz .LBB0_322
.LBB0_371:
	v_max_f32_e32 v66, v67, v22
	v_cmp_gt_u32_e64 s[0:1], v153, v1
	s_nop 0
	v_cndmask_b32_e64 v66, v66, v67, s[0:1]
	v_max_f32_e32 v67, v66, v23
	v_cmp_gt_u32_e64 s[0:1], v154, v1
	s_nop 0
	v_cndmask_b32_e64 v66, v67, v66, s[0:1]
	v_max_f32_e32 v67, v66, v24
	v_cmp_gt_u32_e64 s[0:1], v155, v1
	v_max_f32_e32 v68, v25, v25
	s_nop 0
	v_cndmask_b32_e64 v66, v67, v66, s[0:1]
	v_max_f32_e32 v67, v66, v68
	v_cmp_gt_u32_e64 s[0:1], v156, v1
	s_nop 1
	v_cndmask_b32_e64 v67, v67, v66, s[0:1]
	s_or_b64 exec, exec, s[96:97]
	s_and_saveexec_b64 s[96:97], s[36:37]
	s_cbranch_execz .LBB0_323
.LBB0_372:
	v_max_f32_e32 v66, v67, v10
	v_cmp_gt_u32_e64 s[0:1], v157, v1
	s_nop 0
	v_cndmask_b32_e64 v66, v66, v67, s[0:1]
	v_max_f32_e32 v67, v66, v11
	v_cmp_gt_u32_e64 s[0:1], v158, v1
	s_nop 0
	v_cndmask_b32_e64 v66, v67, v66, s[0:1]
	v_max_f32_e32 v67, v66, v12
	v_cmp_gt_u32_e64 s[0:1], v159, v1
	v_max_f32_e32 v68, v13, v13
	s_nop 0
	v_cndmask_b32_e64 v66, v67, v66, s[0:1]
	v_max_f32_e32 v67, v66, v68
	v_cmp_gt_u32_e64 s[0:1], v160, v1
	s_nop 1
	v_cndmask_b32_e64 v67, v67, v66, s[0:1]
	s_or_b64 exec, exec, s[96:97]
	s_and_saveexec_b64 s[96:97], s[20:21]
	s_cbranch_execz .LBB0_324
.LBB0_373:
	v_max_f32_e32 v66, v67, v18
	v_cmp_gt_u32_e64 s[0:1], v161, v1
	s_nop 0
	v_cndmask_b32_e64 v66, v66, v67, s[0:1]
	v_max_f32_e32 v67, v66, v19
	v_cmp_gt_u32_e64 s[0:1], v162, v1
	s_nop 0
	v_cndmask_b32_e64 v66, v67, v66, s[0:1]
	v_max_f32_e32 v67, v66, v20
	v_cmp_gt_u32_e64 s[0:1], v163, v1
	v_max_f32_e32 v68, v21, v21
	s_nop 0
	v_cndmask_b32_e64 v66, v67, v66, s[0:1]
	v_max_f32_e32 v67, v66, v68
	v_cmp_gt_u32_e64 s[0:1], v164, v1
	s_nop 1
	v_cndmask_b32_e64 v67, v67, v66, s[0:1]
	s_or_b64 exec, exec, s[96:97]
	s_and_saveexec_b64 s[96:97], s[34:35]
	s_cbranch_execz .LBB0_325
.LBB0_374:
	v_max_f32_e32 v66, v67, v6
	v_cmp_gt_u32_e64 s[0:1], v165, v1
	s_nop 0
	v_cndmask_b32_e64 v66, v66, v67, s[0:1]
	v_max_f32_e32 v67, v66, v7
	v_cmp_gt_u32_e64 s[0:1], v166, v1
	s_nop 0
	v_cndmask_b32_e64 v66, v67, v66, s[0:1]
	v_max_f32_e32 v67, v66, v8
	v_cmp_gt_u32_e64 s[0:1], v167, v1
	v_max_f32_e32 v68, v9, v9
	s_nop 0
	v_cndmask_b32_e64 v66, v67, v66, s[0:1]
	v_max_f32_e32 v67, v66, v68
	v_cmp_gt_u32_e64 s[0:1], v168, v1
	s_nop 1
	v_cndmask_b32_e64 v67, v67, v66, s[0:1]
	s_or_b64 exec, exec, s[96:97]
	s_and_saveexec_b64 s[96:97], s[18:19]
	s_cbranch_execz .LBB0_326
.LBB0_375:
	v_max_f32_e32 v66, v67, v14
	v_cmp_gt_u32_e64 s[0:1], v169, v1
	s_nop 0
	v_cndmask_b32_e64 v66, v66, v67, s[0:1]
	v_max_f32_e32 v67, v66, v15
	v_cmp_gt_u32_e64 s[0:1], v170, v1
	s_nop 0
	v_cndmask_b32_e64 v66, v67, v66, s[0:1]
	v_max_f32_e32 v67, v66, v16
	v_cmp_gt_u32_e64 s[0:1], v171, v1
	v_max_f32_e32 v68, v17, v17
	s_nop 0
	v_cndmask_b32_e64 v66, v67, v66, s[0:1]
	v_max_f32_e32 v67, v66, v68
	v_cmp_gt_u32_e64 s[0:1], v172, v1
	s_nop 1
	v_cndmask_b32_e64 v67, v67, v66, s[0:1]
	s_or_b64 exec, exec, s[96:97]
	s_and_saveexec_b64 s[96:97], s[30:31]
	s_cbranch_execnz .LBB0_327
	s_branch .LBB0_328
